# grid barrier: XCD-local release (no L2 write-back / cross-XCD hop) after gate/up->down, w_out->gate/up, down->next gate/up; enabled when each blockIdx&7 group sits on one XCC (run-time check)
# baseline (speedup 1.0000x reference)
; #define LAS __attribute__((address_space(3)))
; __device__ __forceinline__ unsigned xb_add(unsigned* p, unsigned v) { return __hip_atomic_fetch_add(p, v, __ATOMIC_RELAXED, __HIP_MEMORY_SCOPE_AGENT); }
; __device__ __forceinline__ unsigned xb_xcc_id() { return (unsigned)__builtin_amdgcn_s_getreg((3 << 11) | 20) & 0xFu; }
; __device__ __forceinline__ XcdBarrier xcd_barrier_post(unsigned* bar, volatile LAS unsigned* st) {
;     XcdBarrier b; b.bar = bar; b.x = xb_xcc_id(); b.st = st;
;     if (threadIdx.x == 0) (void)xb_add(&bar[XB_XCNT(b.x)], 1u);
;     return b;
; }
.LBB0_644:
	s_or_b64 exec, exec, s[0:1]
	s_add_u32 s0, s78, 0x1e741000
	s_addc_u32 s1, s79, 0
	v_writelane_b32 v253, s0, 2
	s_barrier
	s_nop 0
	v_writelane_b32 v253, s1, 3
	s_getreg_b32 s4, hwreg(HW_REG_XCC_ID, 0, 4)
	s_mov_b32 s81, 0
	v_writelane_b32 v255, s81, 61
	v_cmp_eq_u32_e64 s[2:3], 0, v66
	s_mov_b64 s[0:1], exec
	s_nop 0
	v_writelane_b32 v253, s2, 4
	s_nop 1
	v_writelane_b32 v253, s3, 5
	s_and_b64 s[2:3], s[0:1], s[2:3]
	s_mov_b64 exec, s[2:3]
	s_cbranch_execz .LBB0_647
	s_mov_b64 s[2:3], exec
	v_mbcnt_lo_u32_b32 v0, s2, 0
	v_mbcnt_hi_u32_b32 v0, s3, v0
	v_cmp_eq_u32_e32 vcc, 0, v0
	s_and_b64 s[6:7], exec, vcc
	s_mov_b64 exec, s[6:7]
	s_cbranch_execz .LBB0_647
	s_lshl_b32 s4, s4, 8
	s_bcnt1_i32_b64 s2, s[2:3]
	s_and_b32 s4, s4, 0xf00
	v_mov_b32_e32 v1, s2
	v_readlane_b32 s2, v253, 2
	v_mov_b32_e32 v0, s4
	v_readlane_b32 s3, v253, 3
	s_nop 4
	global_atomic_add v0, v1, s[2:3] offset:1024
	v_readlane_b32 s5, v253, 0
	s_lshr_b32 s4, s4, 8
	s_and_b32 s5, s5, 7
	s_lshl_b32 s5, s5, 2
	s_add_i32 s5, s5, 0x220
	s_lshl_b32 s4, 1, s4
	v_mov_b32_e32 v0, s4
	v_mov_b32_e32 v1, s5
	global_atomic_or v1, v0, s[2:3]

; __device__ __forceinline__ void xcd_barrier(const XcdBarrier& b) {
;     asm volatile("s_waitcnt vmcnt(0)" ::: "memory");
;     __syncthreads();
;     if (threadIdx.x == 0) {
;         unsigned* bar = b.bar;
;         __builtin_amdgcn_s_waitcnt(0);
;         unsigned nloc = b.st[0], nx = b.st[1];
;         if (nloc == 0u) { xcd_barrier_complete(bar, b.x, nloc, nx); b.st[0] = nloc; b.st[1] = nx; }
.LBB0_2979:
	v_readlane_b32 s6, v255, 61
	s_cmp_lg_u32 s6, 0
	s_cbranch_scc1 .Lxl_decided
	v_readlane_b32 s6, v254, 53
	s_cmp_lt_u32 s6, 2
	s_cbranch_scc1 .Lxl_decided
	v_readlane_b32 s6, v253, 2
	v_readlane_b32 s7, v253, 3
	s_nop 4
	global_load_dwordx4 v[20:23], v215, s[6:7] offset:544 sc1
	global_load_dwordx4 v[24:27], v215, s[6:7] offset:560 sc1
	s_waitcnt vmcnt(0)
	s_mov_b32 s6, 0
	s_mov_b32 s7, 1
	v_readfirstlane_b32 s8, v20
	s_add_i32 s9, s8, -1
	s_and_b32 s9, s9, s8
	s_cmp_lg_u32 s9, 0
	s_cselect_b32 s7, 0, s7
	s_cmp_eq_u32 s8, 0
	s_cselect_b32 s7, 0, s7
	s_or_b32 s6, s6, s8
	v_readfirstlane_b32 s8, v21
	s_add_i32 s9, s8, -1
	s_and_b32 s9, s9, s8
	s_cmp_lg_u32 s9, 0
	s_cselect_b32 s7, 0, s7
	s_cmp_eq_u32 s8, 0
	s_cselect_b32 s7, 0, s7
	s_or_b32 s6, s6, s8
	v_readfirstlane_b32 s8, v22
	s_add_i32 s9, s8, -1
	s_and_b32 s9, s9, s8
	s_cmp_lg_u32 s9, 0
	s_cselect_b32 s7, 0, s7
	s_cmp_eq_u32 s8, 0
	s_cselect_b32 s7, 0, s7
	s_or_b32 s6, s6, s8
	v_readfirstlane_b32 s8, v23
	s_add_i32 s9, s8, -1
	s_and_b32 s9, s9, s8
	s_cmp_lg_u32 s9, 0
	s_cselect_b32 s7, 0, s7
	s_cmp_eq_u32 s8, 0
	s_cselect_b32 s7, 0, s7
	s_or_b32 s6, s6, s8
	v_readfirstlane_b32 s8, v24
	s_add_i32 s9, s8, -1
	s_and_b32 s9, s9, s8
	s_cmp_lg_u32 s9, 0
	s_cselect_b32 s7, 0, s7
	s_cmp_eq_u32 s8, 0
	s_cselect_b32 s7, 0, s7
	s_or_b32 s6, s6, s8
	v_readfirstlane_b32 s8, v25
	s_add_i32 s9, s8, -1
	s_and_b32 s9, s9, s8
	s_cmp_lg_u32 s9, 0
	s_cselect_b32 s7, 0, s7
	s_cmp_eq_u32 s8, 0
	s_cselect_b32 s7, 0, s7
	s_or_b32 s6, s6, s8
	v_readfirstlane_b32 s8, v26
	s_add_i32 s9, s8, -1
	s_and_b32 s9, s9, s8
	s_cmp_lg_u32 s9, 0
	s_cselect_b32 s7, 0, s7
	s_cmp_eq_u32 s8, 0
	s_cselect_b32 s7, 0, s7
	s_or_b32 s6, s6, s8
	v_readfirstlane_b32 s8, v27
	s_add_i32 s9, s8, -1
	s_and_b32 s9, s9, s8
	s_cmp_lg_u32 s9, 0
	s_cselect_b32 s7, 0, s7
	s_cmp_eq_u32 s8, 0
	s_cselect_b32 s7, 0, s7
	s_or_b32 s6, s6, s8
	s_cmp_lg_u32 s6, 0xff
	s_cselect_b32 s7, 0, s7
	s_cmp_eq_u32 s7, 1
	s_cselect_b32 s6, 1, 2
	s_nop 0
	v_writelane_b32 v255, s6, 61
